# in-projection output stores: write-through without the non-temporal hint (the mixer phase re-reads them right away)
# speedup vs baseline: 1.0180x; 1.0044x over previous
.LBB0_634:
	v_readlane_b32 s2, v254, 11
	v_cvt_pk_bf16_f32 v94, v94, v95
	v_cvt_pk_bf16_f32 v95, v96, v97
	v_cvt_pk_bf16_f32 v96, v90, v91
	v_cndmask_b32_e64 v90, 0, 1, s[4:5]
	s_and_b32 s61, s15, 0xffff
	v_and_or_b32 v99, v98, 15, s2
	v_lshrrev_b32_e32 v98, 1, v98
	v_lshlrev_b32_e32 v99, 11, v99
	v_and_b32_e32 v98, 24, v98
	v_or3_b32 v98, v98, v99, s88
	s_mov_b32 s60, s14
	v_lshlrev_b32_e32 v98, 1, v98
	v_cmp_ne_u32_e64 s[6:7], 1, v90
	s_andn2_b64 vcc, exec, s[4:5]
	v_cvt_pk_bf16_f32 v97, v92, v93
	buffer_store_dwordx4 v[94:97], v98, s[60:63], 0 offen sc1
	s_cbranch_vccnz .LBB0_636
	v_mul_f32_e32 v91, 0x3d372713, v82
	v_mul_f32_e32 v91, v82, v91
	v_fma_f32 v91, v82, v91, v82
	v_mul_f32_e32 v91, 0xbfcc422a, v91
	v_mul_f32_e32 v91, 0x3fb8aa3b, v91
	v_exp_f32_e32 v91, v91
	v_mul_f32_e32 v90, 0x3d372713, v86
	v_mul_f32_e32 v90, v86, v90
	v_fma_f32 v90, v86, v90, v86
	v_add_f32_e32 v91, 1.0, v91
	v_rcp_f32_e32 v92, v91
	v_mul_f32_e32 v91, 0x3d372713, v87
	v_mul_f32_e32 v91, v87, v91
	v_fma_f32 v91, v87, v91, v87
	v_mul_f32_e32 v90, 0xbfcc422a, v90
	v_mul_f32_e32 v91, 0xbfcc422a, v91
	v_mul_f32_e32 v90, 0x3fb8aa3b, v90
	v_mul_f32_e32 v91, 0x3fb8aa3b, v91
	v_mul_f32_e32 v95, 0x3d372713, v84
	v_exp_f32_e32 v90, v90
	v_exp_f32_e32 v91, v91
	v_mul_f32_e32 v95, v84, v95
	v_fma_f32 v95, v84, v95, v84
	v_mul_f32_e32 v95, 0xbfcc422a, v95
	v_mul_f32_e32 v95, 0x3fb8aa3b, v95
	v_add_f32_e32 v90, 1.0, v90
	v_add_f32_e32 v91, 1.0, v91
	v_exp_f32_e32 v95, v95
	v_rcp_f32_e32 v90, v90
	v_rcp_f32_e32 v91, v91
	v_mul_f32_e32 v93, 0x3d372713, v83
	v_add_f32_e32 v95, 1.0, v95
	v_mul_f32_e32 v94, 0x3d372713, v88
	v_rcp_f32_e32 v96, v95
	v_mul_f32_e32 v95, 0x3d372713, v89
	v_pk_mul_f32 v[86:87], v[86:87], v[90:91]
	v_mul_f32_e32 v90, 0x3d372713, v85
	v_mul_f32_e32 v93, v83, v93
	v_mul_f32_e32 v94, v88, v94
	v_mul_f32_e32 v95, v89, v95
	v_mul_f32_e32 v90, v85, v90
	v_fma_f32 v93, v83, v93, v83
	v_fma_f32 v94, v88, v94, v88
	v_fma_f32 v95, v89, v95, v89
	v_fma_f32 v90, v85, v90, v85
	v_mul_f32_e32 v93, 0xbfcc422a, v93
	v_mul_f32_e32 v94, 0xbfcc422a, v94
	v_mul_f32_e32 v95, 0xbfcc422a, v95
	v_mul_f32_e32 v90, 0xbfcc422a, v90
	v_mul_f32_e32 v93, 0x3fb8aa3b, v93
	v_mul_f32_e32 v94, 0x3fb8aa3b, v94
	v_mul_f32_e32 v95, 0x3fb8aa3b, v95
	v_mul_f32_e32 v90, 0x3fb8aa3b, v90
	v_exp_f32_e32 v93, v93
	v_exp_f32_e32 v94, v94
	v_exp_f32_e32 v95, v95
	v_exp_f32_e32 v90, v90
	v_add_f32_e32 v93, 1.0, v93
	v_add_f32_e32 v94, 1.0, v94
	v_add_f32_e32 v95, 1.0, v95
	v_add_f32_e32 v90, 1.0, v90
	v_rcp_f32_e32 v93, v93
	v_rcp_f32_e32 v94, v94
	v_rcp_f32_e32 v95, v95
	v_rcp_f32_e32 v97, v90
	v_pk_mul_f32 v[82:83], v[82:83], v[92:93]
	v_pk_mul_f32 v[88:89], v[88:89], v[94:95]
	v_pk_mul_f32 v[84:85], v[84:85], v[96:97]
.LBB0_636:
	s_and_b64 vcc, exec, s[6:7]
	v_cvt_pk_bf16_f32 v86, v86, v87
	v_cvt_pk_bf16_f32 v87, v88, v89
	v_cvt_pk_bf16_f32 v88, v82, v83
	v_cvt_pk_bf16_f32 v89, v84, v85
	buffer_store_dwordx4 v[86:89], v98, s[60:63], 0 offen offset:256 sc1
	s_cbranch_vccnz .LBB0_638
	v_mul_f32_e32 v83, 0x3d372713, v74
	v_mul_f32_e32 v83, v74, v83
	v_fma_f32 v83, v74, v83, v74
	v_mul_f32_e32 v83, 0xbfcc422a, v83
	v_mul_f32_e32 v83, 0x3fb8aa3b, v83
	v_exp_f32_e32 v83, v83
	v_mul_f32_e32 v82, 0x3d372713, v78
	v_mul_f32_e32 v82, v78, v82
	v_fma_f32 v82, v78, v82, v78
	v_add_f32_e32 v83, 1.0, v83
	v_rcp_f32_e32 v84, v83
	v_mul_f32_e32 v83, 0x3d372713, v79
	v_mul_f32_e32 v83, v79, v83
	v_fma_f32 v83, v79, v83, v79
	v_mul_f32_e32 v82, 0xbfcc422a, v82
	v_mul_f32_e32 v83, 0xbfcc422a, v83
	v_mul_f32_e32 v82, 0x3fb8aa3b, v82
	v_mul_f32_e32 v83, 0x3fb8aa3b, v83
	v_mul_f32_e32 v87, 0x3d372713, v76
	v_exp_f32_e32 v82, v82
	v_exp_f32_e32 v83, v83
	v_mul_f32_e32 v87, v76, v87
	v_fma_f32 v87, v76, v87, v76
	v_mul_f32_e32 v87, 0xbfcc422a, v87
	v_mul_f32_e32 v87, 0x3fb8aa3b, v87
	v_add_f32_e32 v82, 1.0, v82
	v_add_f32_e32 v83, 1.0, v83
	v_exp_f32_e32 v87, v87
	v_rcp_f32_e32 v82, v82
	v_rcp_f32_e32 v83, v83
	v_mul_f32_e32 v85, 0x3d372713, v75
	v_add_f32_e32 v87, 1.0, v87
	v_mul_f32_e32 v86, 0x3d372713, v80
	v_rcp_f32_e32 v88, v87
	v_mul_f32_e32 v87, 0x3d372713, v81
	v_pk_mul_f32 v[78:79], v[78:79], v[82:83]
	v_mul_f32_e32 v82, 0x3d372713, v77
	v_mul_f32_e32 v85, v75, v85
	v_mul_f32_e32 v86, v80, v86
	v_mul_f32_e32 v87, v81, v87
	v_mul_f32_e32 v82, v77, v82
	v_fma_f32 v85, v75, v85, v75
	v_fma_f32 v86, v80, v86, v80
	v_fma_f32 v87, v81, v87, v81
	v_fma_f32 v82, v77, v82, v77
	v_mul_f32_e32 v85, 0xbfcc422a, v85
	v_mul_f32_e32 v86, 0xbfcc422a, v86
	v_mul_f32_e32 v87, 0xbfcc422a, v87
	v_mul_f32_e32 v82, 0xbfcc422a, v82
	v_mul_f32_e32 v85, 0x3fb8aa3b, v85
	v_mul_f32_e32 v86, 0x3fb8aa3b, v86
	v_mul_f32_e32 v87, 0x3fb8aa3b, v87
	v_mul_f32_e32 v82, 0x3fb8aa3b, v82
	v_exp_f32_e32 v85, v85
	v_exp_f32_e32 v86, v86
	v_exp_f32_e32 v87, v87
	v_exp_f32_e32 v82, v82
	v_add_f32_e32 v85, 1.0, v85
	v_add_f32_e32 v86, 1.0, v86
	v_add_f32_e32 v87, 1.0, v87
	v_add_f32_e32 v82, 1.0, v82
	v_rcp_f32_e32 v85, v85
	v_rcp_f32_e32 v86, v86
	v_rcp_f32_e32 v87, v87
	v_rcp_f32_e32 v89, v82
	v_pk_mul_f32 v[74:75], v[74:75], v[84:85]
	v_pk_mul_f32 v[80:81], v[80:81], v[86:87]
	v_pk_mul_f32 v[76:77], v[76:77], v[88:89]
.LBB0_638:
	v_add_u32_e32 v82, 0x10000, v98
	s_mov_b32 s60, s14
	s_and_b64 vcc, exec, s[6:7]
	v_cvt_pk_bf16_f32 v78, v78, v79
	v_cvt_pk_bf16_f32 v79, v80, v81
	v_cvt_pk_bf16_f32 v80, v74, v75
	v_cvt_pk_bf16_f32 v81, v76, v77
	buffer_store_dwordx4 v[78:81], v82, s[60:63], 0 offen sc1
	s_cbranch_vccnz .LBB0_640
	v_mul_f32_e32 v75, 0x3d372713, v66
	v_mul_f32_e32 v75, v66, v75
	v_fma_f32 v75, v66, v75, v66
	v_mul_f32_e32 v75, 0xbfcc422a, v75
	v_mul_f32_e32 v75, 0x3fb8aa3b, v75
	v_exp_f32_e32 v75, v75
	v_mul_f32_e32 v74, 0x3d372713, v70
	v_mul_f32_e32 v74, v70, v74
	v_fma_f32 v74, v70, v74, v70
	v_add_f32_e32 v75, 1.0, v75
	v_rcp_f32_e32 v76, v75
	v_mul_f32_e32 v75, 0x3d372713, v71
	v_mul_f32_e32 v75, v71, v75
	v_fma_f32 v75, v71, v75, v71
	v_mul_f32_e32 v74, 0xbfcc422a, v74
	v_mul_f32_e32 v75, 0xbfcc422a, v75
	v_mul_f32_e32 v74, 0x3fb8aa3b, v74
	v_mul_f32_e32 v75, 0x3fb8aa3b, v75
	v_mul_f32_e32 v79, 0x3d372713, v68
	v_exp_f32_e32 v74, v74
	v_exp_f32_e32 v75, v75
	v_mul_f32_e32 v79, v68, v79
	v_fma_f32 v79, v68, v79, v68
	v_mul_f32_e32 v79, 0xbfcc422a, v79
	v_mul_f32_e32 v79, 0x3fb8aa3b, v79
	v_add_f32_e32 v74, 1.0, v74
	v_add_f32_e32 v75, 1.0, v75
	v_exp_f32_e32 v79, v79
	v_rcp_f32_e32 v74, v74
	v_rcp_f32_e32 v75, v75
	v_mul_f32_e32 v77, 0x3d372713, v67
	v_add_f32_e32 v79, 1.0, v79
	v_mul_f32_e32 v78, 0x3d372713, v72
	v_rcp_f32_e32 v80, v79
	v_mul_f32_e32 v79, 0x3d372713, v73
	v_pk_mul_f32 v[70:71], v[70:71], v[74:75]
	v_mul_f32_e32 v74, 0x3d372713, v69
	v_mul_f32_e32 v77, v67, v77
	v_mul_f32_e32 v78, v72, v78
	v_mul_f32_e32 v79, v73, v79
	v_mul_f32_e32 v74, v69, v74
	v_fma_f32 v77, v67, v77, v67
	v_fma_f32 v78, v72, v78, v72
	v_fma_f32 v79, v73, v79, v73
	v_fma_f32 v74, v69, v74, v69
	v_mul_f32_e32 v77, 0xbfcc422a, v77
	v_mul_f32_e32 v78, 0xbfcc422a, v78
	v_mul_f32_e32 v79, 0xbfcc422a, v79
	v_mul_f32_e32 v74, 0xbfcc422a, v74
	v_mul_f32_e32 v77, 0x3fb8aa3b, v77
	v_mul_f32_e32 v78, 0x3fb8aa3b, v78
	v_mul_f32_e32 v79, 0x3fb8aa3b, v79
	v_mul_f32_e32 v74, 0x3fb8aa3b, v74
	v_exp_f32_e32 v77, v77
	v_exp_f32_e32 v78, v78
	v_exp_f32_e32 v79, v79
	v_exp_f32_e32 v74, v74
	v_add_f32_e32 v77, 1.0, v77
	v_add_f32_e32 v78, 1.0, v78
	v_add_f32_e32 v79, 1.0, v79
	v_add_f32_e32 v74, 1.0, v74
	v_rcp_f32_e32 v77, v77
	v_rcp_f32_e32 v78, v78
	v_rcp_f32_e32 v79, v79
	v_rcp_f32_e32 v81, v74
	v_pk_mul_f32 v[66:67], v[66:67], v[76:77]
	v_pk_mul_f32 v[72:73], v[72:73], v[78:79]
	v_pk_mul_f32 v[68:69], v[68:69], v[80:81]
.LBB0_640:
	s_and_b64 vcc, exec, s[6:7]
	v_cvt_pk_bf16_f32 v70, v70, v71
	v_cvt_pk_bf16_f32 v71, v72, v73
	v_cvt_pk_bf16_f32 v72, v66, v67
	v_cvt_pk_bf16_f32 v73, v68, v69
	buffer_store_dwordx4 v[70:73], v82, s[60:63], 0 offen offset:256 sc1
	s_cbranch_vccnz .LBB0_642
	v_mul_f32_e32 v67, 0x3d372713, v58
	v_mul_f32_e32 v67, v58, v67
	v_fma_f32 v67, v58, v67, v58
	v_mul_f32_e32 v67, 0xbfcc422a, v67
	v_mul_f32_e32 v67, 0x3fb8aa3b, v67
	v_exp_f32_e32 v67, v67
	v_mul_f32_e32 v66, 0x3d372713, v62
	v_mul_f32_e32 v66, v62, v66
	v_fma_f32 v66, v62, v66, v62
	v_add_f32_e32 v67, 1.0, v67
	v_rcp_f32_e32 v68, v67
	v_mul_f32_e32 v67, 0x3d372713, v63
	v_mul_f32_e32 v67, v63, v67
	v_fma_f32 v67, v63, v67, v63
	v_mul_f32_e32 v66, 0xbfcc422a, v66
	v_mul_f32_e32 v67, 0xbfcc422a, v67
	v_mul_f32_e32 v66, 0x3fb8aa3b, v66
	v_mul_f32_e32 v67, 0x3fb8aa3b, v67
	v_mul_f32_e32 v71, 0x3d372713, v60
	v_exp_f32_e32 v66, v66
	v_exp_f32_e32 v67, v67
	v_mul_f32_e32 v71, v60, v71
	v_fma_f32 v71, v60, v71, v60
	v_mul_f32_e32 v71, 0xbfcc422a, v71
	v_mul_f32_e32 v71, 0x3fb8aa3b, v71
	v_add_f32_e32 v66, 1.0, v66
	v_add_f32_e32 v67, 1.0, v67
	v_exp_f32_e32 v71, v71
	v_rcp_f32_e32 v66, v66
	v_rcp_f32_e32 v67, v67
	v_mul_f32_e32 v69, 0x3d372713, v59
	v_add_f32_e32 v71, 1.0, v71
	v_mul_f32_e32 v70, 0x3d372713, v64
	v_rcp_f32_e32 v72, v71
	v_mul_f32_e32 v71, 0x3d372713, v65
	v_pk_mul_f32 v[62:63], v[62:63], v[66:67]
	v_mul_f32_e32 v66, 0x3d372713, v61
	v_mul_f32_e32 v69, v59, v69
	v_mul_f32_e32 v70, v64, v70
	v_mul_f32_e32 v71, v65, v71
	v_mul_f32_e32 v66, v61, v66
	v_fma_f32 v69, v59, v69, v59
	v_fma_f32 v70, v64, v70, v64
	v_fma_f32 v71, v65, v71, v65
	v_fma_f32 v66, v61, v66, v61
	v_mul_f32_e32 v69, 0xbfcc422a, v69
	v_mul_f32_e32 v70, 0xbfcc422a, v70
	v_mul_f32_e32 v71, 0xbfcc422a, v71
	v_mul_f32_e32 v66, 0xbfcc422a, v66
	v_mul_f32_e32 v69, 0x3fb8aa3b, v69
	v_mul_f32_e32 v70, 0x3fb8aa3b, v70
	v_mul_f32_e32 v71, 0x3fb8aa3b, v71
	v_mul_f32_e32 v66, 0x3fb8aa3b, v66
	v_exp_f32_e32 v69, v69
	v_exp_f32_e32 v70, v70
	v_exp_f32_e32 v71, v71
	v_exp_f32_e32 v66, v66
	v_add_f32_e32 v69, 1.0, v69
	v_add_f32_e32 v70, 1.0, v70
	v_add_f32_e32 v71, 1.0, v71
	v_add_f32_e32 v66, 1.0, v66
	v_rcp_f32_e32 v69, v69
	v_rcp_f32_e32 v70, v70
	v_rcp_f32_e32 v71, v71
	v_rcp_f32_e32 v73, v66
	v_pk_mul_f32 v[58:59], v[58:59], v[68:69]
	v_pk_mul_f32 v[64:65], v[64:65], v[70:71]
	v_pk_mul_f32 v[60:61], v[60:61], v[72:73]
.LBB0_642:
	v_add_u32_e32 v66, 0x20000, v98
	s_mov_b32 s60, s14
	s_and_b64 vcc, exec, s[6:7]
	v_cvt_pk_bf16_f32 v62, v62, v63
	v_cvt_pk_bf16_f32 v63, v64, v65
	v_cvt_pk_bf16_f32 v64, v58, v59
	v_cvt_pk_bf16_f32 v65, v60, v61
	buffer_store_dwordx4 v[62:65], v66, s[60:63], 0 offen sc1
	s_cbranch_vccnz .LBB0_644
	v_mul_f32_e32 v59, 0x3d372713, v50
	v_mul_f32_e32 v59, v50, v59
	v_fma_f32 v59, v50, v59, v50
	v_mul_f32_e32 v59, 0xbfcc422a, v59
	v_mul_f32_e32 v59, 0x3fb8aa3b, v59
	v_exp_f32_e32 v59, v59
	v_mul_f32_e32 v58, 0x3d372713, v54
	v_mul_f32_e32 v58, v54, v58
	v_fma_f32 v58, v54, v58, v54
	v_add_f32_e32 v59, 1.0, v59
	v_rcp_f32_e32 v60, v59
	v_mul_f32_e32 v59, 0x3d372713, v55
	v_mul_f32_e32 v59, v55, v59
	v_fma_f32 v59, v55, v59, v55
	v_mul_f32_e32 v58, 0xbfcc422a, v58
	v_mul_f32_e32 v59, 0xbfcc422a, v59
	v_mul_f32_e32 v58, 0x3fb8aa3b, v58
	v_mul_f32_e32 v59, 0x3fb8aa3b, v59
	v_mul_f32_e32 v63, 0x3d372713, v52
	v_exp_f32_e32 v58, v58
	v_exp_f32_e32 v59, v59
	v_mul_f32_e32 v63, v52, v63
	v_fma_f32 v63, v52, v63, v52
	v_mul_f32_e32 v63, 0xbfcc422a, v63
	v_mul_f32_e32 v63, 0x3fb8aa3b, v63
	v_add_f32_e32 v58, 1.0, v58
	v_add_f32_e32 v59, 1.0, v59
	v_exp_f32_e32 v63, v63
	v_rcp_f32_e32 v58, v58
	v_rcp_f32_e32 v59, v59
	v_mul_f32_e32 v61, 0x3d372713, v51
	v_add_f32_e32 v63, 1.0, v63
	v_mul_f32_e32 v62, 0x3d372713, v56
	v_rcp_f32_e32 v64, v63
	v_mul_f32_e32 v63, 0x3d372713, v57
	v_pk_mul_f32 v[54:55], v[54:55], v[58:59]
	v_mul_f32_e32 v58, 0x3d372713, v53
	v_mul_f32_e32 v61, v51, v61
	v_mul_f32_e32 v62, v56, v62
	v_mul_f32_e32 v63, v57, v63
	v_mul_f32_e32 v58, v53, v58
	v_fma_f32 v61, v51, v61, v51
	v_fma_f32 v62, v56, v62, v56
	v_fma_f32 v63, v57, v63, v57
	v_fma_f32 v58, v53, v58, v53
	v_mul_f32_e32 v61, 0xbfcc422a, v61
	v_mul_f32_e32 v62, 0xbfcc422a, v62
	v_mul_f32_e32 v63, 0xbfcc422a, v63
	v_mul_f32_e32 v58, 0xbfcc422a, v58
	v_mul_f32_e32 v61, 0x3fb8aa3b, v61
	v_mul_f32_e32 v62, 0x3fb8aa3b, v62
	v_mul_f32_e32 v63, 0x3fb8aa3b, v63
	v_mul_f32_e32 v58, 0x3fb8aa3b, v58
	v_exp_f32_e32 v61, v61
	v_exp_f32_e32 v62, v62
	v_exp_f32_e32 v63, v63
	v_exp_f32_e32 v58, v58
	v_add_f32_e32 v61, 1.0, v61
	v_add_f32_e32 v62, 1.0, v62
	v_add_f32_e32 v63, 1.0, v63
	v_add_f32_e32 v58, 1.0, v58
	v_rcp_f32_e32 v61, v61
	v_rcp_f32_e32 v62, v62
	v_rcp_f32_e32 v63, v63
	v_rcp_f32_e32 v65, v58
	v_pk_mul_f32 v[50:51], v[50:51], v[60:61]
	v_pk_mul_f32 v[56:57], v[56:57], v[62:63]
	v_pk_mul_f32 v[52:53], v[52:53], v[64:65]
.LBB0_644:
	s_and_b64 vcc, exec, s[6:7]
	v_cvt_pk_bf16_f32 v54, v54, v55
	v_cvt_pk_bf16_f32 v55, v56, v57
	v_cvt_pk_bf16_f32 v56, v50, v51
	v_cvt_pk_bf16_f32 v57, v52, v53
	buffer_store_dwordx4 v[54:57], v66, s[60:63], 0 offen offset:256 sc1
	s_cbranch_vccnz .LBB0_646
	v_mul_f32_e32 v51, 0x3d372713, v42
	v_mul_f32_e32 v51, v42, v51
	v_fma_f32 v51, v42, v51, v42
	v_mul_f32_e32 v51, 0xbfcc422a, v51
	v_mul_f32_e32 v51, 0x3fb8aa3b, v51
	v_exp_f32_e32 v51, v51
	v_mul_f32_e32 v50, 0x3d372713, v46
	v_mul_f32_e32 v50, v46, v50
	v_fma_f32 v50, v46, v50, v46
	v_add_f32_e32 v51, 1.0, v51
	v_rcp_f32_e32 v52, v51
	v_mul_f32_e32 v51, 0x3d372713, v47
	v_mul_f32_e32 v51, v47, v51
	v_fma_f32 v51, v47, v51, v47
	v_mul_f32_e32 v50, 0xbfcc422a, v50
	v_mul_f32_e32 v51, 0xbfcc422a, v51
	v_mul_f32_e32 v50, 0x3fb8aa3b, v50
	v_mul_f32_e32 v51, 0x3fb8aa3b, v51
	v_mul_f32_e32 v55, 0x3d372713, v44
	v_exp_f32_e32 v50, v50
	v_exp_f32_e32 v51, v51
	v_mul_f32_e32 v55, v44, v55
	v_fma_f32 v55, v44, v55, v44
	v_mul_f32_e32 v55, 0xbfcc422a, v55
	v_mul_f32_e32 v55, 0x3fb8aa3b, v55
	v_add_f32_e32 v50, 1.0, v50
	v_add_f32_e32 v51, 1.0, v51
	v_exp_f32_e32 v55, v55
	v_rcp_f32_e32 v50, v50
	v_rcp_f32_e32 v51, v51
	v_mul_f32_e32 v53, 0x3d372713, v43
	v_add_f32_e32 v55, 1.0, v55
	v_mul_f32_e32 v54, 0x3d372713, v48
	v_rcp_f32_e32 v56, v55
	v_mul_f32_e32 v55, 0x3d372713, v49
	v_pk_mul_f32 v[46:47], v[46:47], v[50:51]
	v_mul_f32_e32 v50, 0x3d372713, v45
	v_mul_f32_e32 v53, v43, v53
	v_mul_f32_e32 v54, v48, v54
	v_mul_f32_e32 v55, v49, v55
	v_mul_f32_e32 v50, v45, v50
	v_fma_f32 v53, v43, v53, v43
	v_fma_f32 v54, v48, v54, v48
	v_fma_f32 v55, v49, v55, v49
	v_fma_f32 v50, v45, v50, v45
	v_mul_f32_e32 v53, 0xbfcc422a, v53
	v_mul_f32_e32 v54, 0xbfcc422a, v54
	v_mul_f32_e32 v55, 0xbfcc422a, v55
	v_mul_f32_e32 v50, 0xbfcc422a, v50
	v_mul_f32_e32 v53, 0x3fb8aa3b, v53
	v_mul_f32_e32 v54, 0x3fb8aa3b, v54
	v_mul_f32_e32 v55, 0x3fb8aa3b, v55
	v_mul_f32_e32 v50, 0x3fb8aa3b, v50
	v_exp_f32_e32 v53, v53
	v_exp_f32_e32 v54, v54
	v_exp_f32_e32 v55, v55
	v_exp_f32_e32 v50, v50
	v_add_f32_e32 v53, 1.0, v53
	v_add_f32_e32 v54, 1.0, v54
	v_add_f32_e32 v55, 1.0, v55
	v_add_f32_e32 v50, 1.0, v50
	v_rcp_f32_e32 v53, v53
	v_rcp_f32_e32 v54, v54
	v_rcp_f32_e32 v55, v55
	v_rcp_f32_e32 v57, v50
	v_pk_mul_f32 v[42:43], v[42:43], v[52:53]
	v_pk_mul_f32 v[48:49], v[48:49], v[54:55]
	v_pk_mul_f32 v[44:45], v[44:45], v[56:57]
.LBB0_646:
	v_add_u32_e32 v50, 0x60000, v98
	s_mov_b32 s60, s14
	s_and_b64 vcc, exec, s[6:7]
	v_cvt_pk_bf16_f32 v46, v46, v47
	v_cvt_pk_bf16_f32 v47, v48, v49
	v_cvt_pk_bf16_f32 v48, v42, v43
	v_cvt_pk_bf16_f32 v49, v44, v45
	buffer_store_dwordx4 v[46:49], v50, s[60:63], 0 offen sc1
	s_cbranch_vccnz .LBB0_648
	v_mul_f32_e32 v43, 0x3d372713, v34
	v_mul_f32_e32 v43, v34, v43
	v_fma_f32 v43, v34, v43, v34
	v_mul_f32_e32 v43, 0xbfcc422a, v43
	v_mul_f32_e32 v43, 0x3fb8aa3b, v43
	v_exp_f32_e32 v43, v43
	v_mul_f32_e32 v42, 0x3d372713, v38
	v_mul_f32_e32 v42, v38, v42
	v_fma_f32 v42, v38, v42, v38
	v_add_f32_e32 v43, 1.0, v43
	v_rcp_f32_e32 v44, v43
	v_mul_f32_e32 v43, 0x3d372713, v39
	v_mul_f32_e32 v43, v39, v43
	v_fma_f32 v43, v39, v43, v39
	v_mul_f32_e32 v42, 0xbfcc422a, v42
	v_mul_f32_e32 v43, 0xbfcc422a, v43
	v_mul_f32_e32 v42, 0x3fb8aa3b, v42
	v_mul_f32_e32 v43, 0x3fb8aa3b, v43
	v_mul_f32_e32 v47, 0x3d372713, v36
	v_exp_f32_e32 v42, v42
	v_exp_f32_e32 v43, v43
	v_mul_f32_e32 v47, v36, v47
	v_fma_f32 v47, v36, v47, v36
	v_mul_f32_e32 v47, 0xbfcc422a, v47
	v_mul_f32_e32 v47, 0x3fb8aa3b, v47
	v_add_f32_e32 v42, 1.0, v42
	v_add_f32_e32 v43, 1.0, v43
	v_exp_f32_e32 v47, v47
	v_rcp_f32_e32 v42, v42
	v_rcp_f32_e32 v43, v43
	v_mul_f32_e32 v45, 0x3d372713, v35
	v_add_f32_e32 v47, 1.0, v47
	v_mul_f32_e32 v46, 0x3d372713, v40
	v_rcp_f32_e32 v48, v47
	v_mul_f32_e32 v47, 0x3d372713, v41
	v_pk_mul_f32 v[38:39], v[38:39], v[42:43]
	v_mul_f32_e32 v42, 0x3d372713, v37
	v_mul_f32_e32 v45, v35, v45
	v_mul_f32_e32 v46, v40, v46
	v_mul_f32_e32 v47, v41, v47
	v_mul_f32_e32 v42, v37, v42
	v_fma_f32 v45, v35, v45, v35
	v_fma_f32 v46, v40, v46, v40
	v_fma_f32 v47, v41, v47, v41
	v_fma_f32 v42, v37, v42, v37
	v_mul_f32_e32 v45, 0xbfcc422a, v45
	v_mul_f32_e32 v46, 0xbfcc422a, v46
	v_mul_f32_e32 v47, 0xbfcc422a, v47
	v_mul_f32_e32 v42, 0xbfcc422a, v42
	v_mul_f32_e32 v45, 0x3fb8aa3b, v45
	v_mul_f32_e32 v46, 0x3fb8aa3b, v46
	v_mul_f32_e32 v47, 0x3fb8aa3b, v47
	v_mul_f32_e32 v42, 0x3fb8aa3b, v42
	v_exp_f32_e32 v45, v45
	v_exp_f32_e32 v46, v46
	v_exp_f32_e32 v47, v47
	v_exp_f32_e32 v42, v42
	v_add_f32_e32 v45, 1.0, v45
	v_add_f32_e32 v46, 1.0, v46
	v_add_f32_e32 v47, 1.0, v47
	v_add_f32_e32 v42, 1.0, v42
	v_rcp_f32_e32 v45, v45
	v_rcp_f32_e32 v46, v46
	v_rcp_f32_e32 v47, v47
	v_rcp_f32_e32 v49, v42
	v_pk_mul_f32 v[34:35], v[34:35], v[44:45]
	v_pk_mul_f32 v[40:41], v[40:41], v[46:47]
	v_pk_mul_f32 v[36:37], v[36:37], v[48:49]
.LBB0_648:
	s_and_b64 vcc, exec, s[6:7]
	v_cvt_pk_bf16_f32 v38, v38, v39
	v_cvt_pk_bf16_f32 v39, v40, v41
	v_cvt_pk_bf16_f32 v40, v34, v35
	v_cvt_pk_bf16_f32 v41, v36, v37
	buffer_store_dwordx4 v[38:41], v50, s[60:63], 0 offen offset:256 sc1
	s_cbranch_vccnz .LBB0_650
	v_mul_f32_e32 v35, 0x3d372713, v26
	v_mul_f32_e32 v35, v26, v35
	v_fma_f32 v35, v26, v35, v26
	v_mul_f32_e32 v35, 0xbfcc422a, v35
	v_mul_f32_e32 v35, 0x3fb8aa3b, v35
	v_exp_f32_e32 v35, v35
	v_mul_f32_e32 v34, 0x3d372713, v30
	v_mul_f32_e32 v34, v30, v34
	v_fma_f32 v34, v30, v34, v30
	v_add_f32_e32 v35, 1.0, v35
	v_rcp_f32_e32 v36, v35
	v_mul_f32_e32 v35, 0x3d372713, v31
	v_mul_f32_e32 v35, v31, v35
	v_fma_f32 v35, v31, v35, v31
	v_mul_f32_e32 v34, 0xbfcc422a, v34
	v_mul_f32_e32 v35, 0xbfcc422a, v35
	v_mul_f32_e32 v34, 0x3fb8aa3b, v34
	v_mul_f32_e32 v35, 0x3fb8aa3b, v35
	v_mul_f32_e32 v39, 0x3d372713, v28
	v_exp_f32_e32 v34, v34
	v_exp_f32_e32 v35, v35
	v_mul_f32_e32 v39, v28, v39
	v_fma_f32 v39, v28, v39, v28
	v_mul_f32_e32 v39, 0xbfcc422a, v39
	v_mul_f32_e32 v39, 0x3fb8aa3b, v39
	v_add_f32_e32 v34, 1.0, v34
	v_add_f32_e32 v35, 1.0, v35
	v_exp_f32_e32 v39, v39
	v_rcp_f32_e32 v34, v34
	v_rcp_f32_e32 v35, v35
	v_mul_f32_e32 v37, 0x3d372713, v27
	v_add_f32_e32 v39, 1.0, v39
	v_mul_f32_e32 v38, 0x3d372713, v32
	v_rcp_f32_e32 v40, v39
	v_mul_f32_e32 v39, 0x3d372713, v33
	v_pk_mul_f32 v[30:31], v[30:31], v[34:35]
	v_mul_f32_e32 v34, 0x3d372713, v29
	v_mul_f32_e32 v37, v27, v37
	v_mul_f32_e32 v38, v32, v38
	v_mul_f32_e32 v39, v33, v39
	v_mul_f32_e32 v34, v29, v34
	v_fma_f32 v37, v27, v37, v27
	v_fma_f32 v38, v32, v38, v32
	v_fma_f32 v39, v33, v39, v33
	v_fma_f32 v34, v29, v34, v29
	v_mul_f32_e32 v37, 0xbfcc422a, v37
	v_mul_f32_e32 v38, 0xbfcc422a, v38
	v_mul_f32_e32 v39, 0xbfcc422a, v39
	v_mul_f32_e32 v34, 0xbfcc422a, v34
	v_mul_f32_e32 v37, 0x3fb8aa3b, v37
	v_mul_f32_e32 v38, 0x3fb8aa3b, v38
	v_mul_f32_e32 v39, 0x3fb8aa3b, v39
	v_mul_f32_e32 v34, 0x3fb8aa3b, v34
	v_exp_f32_e32 v37, v37
	v_exp_f32_e32 v38, v38
	v_exp_f32_e32 v39, v39
	v_exp_f32_e32 v34, v34
	v_add_f32_e32 v37, 1.0, v37
	v_add_f32_e32 v38, 1.0, v38
	v_add_f32_e32 v39, 1.0, v39
	v_add_f32_e32 v34, 1.0, v34
	v_rcp_f32_e32 v37, v37
	v_rcp_f32_e32 v38, v38
	v_rcp_f32_e32 v39, v39
	v_rcp_f32_e32 v41, v34
	v_pk_mul_f32 v[26:27], v[26:27], v[36:37]
	v_pk_mul_f32 v[32:33], v[32:33], v[38:39]
	v_pk_mul_f32 v[28:29], v[28:29], v[40:41]
.LBB0_650:
	v_add_u32_e32 v34, 0x70000, v98
	s_mov_b32 s60, s14
	s_and_b64 vcc, exec, s[6:7]
	v_cvt_pk_bf16_f32 v30, v30, v31
	v_cvt_pk_bf16_f32 v31, v32, v33
	v_cvt_pk_bf16_f32 v32, v26, v27
	v_cvt_pk_bf16_f32 v33, v28, v29
	buffer_store_dwordx4 v[30:33], v34, s[60:63], 0 offen sc1
	s_cbranch_vccnz .LBB0_652
	v_mul_f32_e32 v27, 0x3d372713, v18
	v_mul_f32_e32 v27, v18, v27
	v_fma_f32 v27, v18, v27, v18
	v_mul_f32_e32 v27, 0xbfcc422a, v27
	v_mul_f32_e32 v27, 0x3fb8aa3b, v27
	v_exp_f32_e32 v27, v27
	v_mul_f32_e32 v26, 0x3d372713, v22
	v_mul_f32_e32 v26, v22, v26
	v_fma_f32 v26, v22, v26, v22
	v_add_f32_e32 v27, 1.0, v27
	v_rcp_f32_e32 v28, v27
	v_mul_f32_e32 v27, 0x3d372713, v23
	v_mul_f32_e32 v27, v23, v27
	v_fma_f32 v27, v23, v27, v23
	v_mul_f32_e32 v26, 0xbfcc422a, v26
	v_mul_f32_e32 v27, 0xbfcc422a, v27
	v_mul_f32_e32 v26, 0x3fb8aa3b, v26
	v_mul_f32_e32 v27, 0x3fb8aa3b, v27
	v_mul_f32_e32 v31, 0x3d372713, v20
	v_exp_f32_e32 v26, v26
	v_exp_f32_e32 v27, v27
	v_mul_f32_e32 v31, v20, v31
	v_fma_f32 v31, v20, v31, v20
	v_mul_f32_e32 v31, 0xbfcc422a, v31
	v_mul_f32_e32 v31, 0x3fb8aa3b, v31
	v_add_f32_e32 v26, 1.0, v26
	v_add_f32_e32 v27, 1.0, v27
	v_exp_f32_e32 v31, v31
	v_rcp_f32_e32 v26, v26
	v_rcp_f32_e32 v27, v27
	v_mul_f32_e32 v29, 0x3d372713, v19
	v_add_f32_e32 v31, 1.0, v31
	v_mul_f32_e32 v30, 0x3d372713, v24
	v_rcp_f32_e32 v32, v31
	v_mul_f32_e32 v31, 0x3d372713, v25
	v_pk_mul_f32 v[22:23], v[22:23], v[26:27]
	v_mul_f32_e32 v26, 0x3d372713, v21
	v_mul_f32_e32 v29, v19, v29
	v_mul_f32_e32 v30, v24, v30
	v_mul_f32_e32 v31, v25, v31
	v_mul_f32_e32 v26, v21, v26
	v_fma_f32 v29, v19, v29, v19
	v_fma_f32 v30, v24, v30, v24
	v_fma_f32 v31, v25, v31, v25
	v_fma_f32 v26, v21, v26, v21
	v_mul_f32_e32 v29, 0xbfcc422a, v29
	v_mul_f32_e32 v30, 0xbfcc422a, v30
	v_mul_f32_e32 v31, 0xbfcc422a, v31
	v_mul_f32_e32 v26, 0xbfcc422a, v26
	v_mul_f32_e32 v29, 0x3fb8aa3b, v29
	v_mul_f32_e32 v30, 0x3fb8aa3b, v30
	v_mul_f32_e32 v31, 0x3fb8aa3b, v31
	v_mul_f32_e32 v26, 0x3fb8aa3b, v26
	v_exp_f32_e32 v29, v29
	v_exp_f32_e32 v30, v30
	v_exp_f32_e32 v31, v31
	v_exp_f32_e32 v26, v26
	v_add_f32_e32 v29, 1.0, v29
	v_add_f32_e32 v30, 1.0, v30
	v_add_f32_e32 v31, 1.0, v31
	v_add_f32_e32 v26, 1.0, v26
	v_rcp_f32_e32 v29, v29
	v_rcp_f32_e32 v30, v30
	v_rcp_f32_e32 v31, v31
	v_rcp_f32_e32 v33, v26
	v_pk_mul_f32 v[18:19], v[18:19], v[28:29]
	v_pk_mul_f32 v[24:25], v[24:25], v[30:31]
	v_pk_mul_f32 v[20:21], v[20:21], v[32:33]
.LBB0_652:
	s_and_b64 vcc, exec, s[6:7]
	v_cvt_pk_bf16_f32 v22, v22, v23
	v_cvt_pk_bf16_f32 v23, v24, v25
	v_cvt_pk_bf16_f32 v24, v18, v19
	v_cvt_pk_bf16_f32 v25, v20, v21
	buffer_store_dwordx4 v[22:25], v34, s[60:63], 0 offen offset:256 sc1
	s_cbranch_vccnz .LBB0_654
	v_mul_f32_e32 v19, 0x3d372713, v10
	v_mul_f32_e32 v19, v10, v19
	v_fma_f32 v19, v10, v19, v10
	v_mul_f32_e32 v19, 0xbfcc422a, v19
	v_mul_f32_e32 v19, 0x3fb8aa3b, v19
	v_exp_f32_e32 v19, v19
	v_mul_f32_e32 v18, 0x3d372713, v14
	v_mul_f32_e32 v18, v14, v18
	v_fma_f32 v18, v14, v18, v14
	v_add_f32_e32 v19, 1.0, v19
	v_rcp_f32_e32 v20, v19
	v_mul_f32_e32 v19, 0x3d372713, v15
	v_mul_f32_e32 v19, v15, v19
	v_fma_f32 v19, v15, v19, v15
	v_mul_f32_e32 v18, 0xbfcc422a, v18
	v_mul_f32_e32 v19, 0xbfcc422a, v19
	v_mul_f32_e32 v18, 0x3fb8aa3b, v18
	v_mul_f32_e32 v19, 0x3fb8aa3b, v19
	v_mul_f32_e32 v23, 0x3d372713, v12
	v_exp_f32_e32 v18, v18
	v_exp_f32_e32 v19, v19
	v_mul_f32_e32 v23, v12, v23
	v_fma_f32 v23, v12, v23, v12
	v_mul_f32_e32 v23, 0xbfcc422a, v23
	v_mul_f32_e32 v23, 0x3fb8aa3b, v23
	v_add_f32_e32 v18, 1.0, v18
	v_add_f32_e32 v19, 1.0, v19
	v_exp_f32_e32 v23, v23
	v_rcp_f32_e32 v18, v18
	v_rcp_f32_e32 v19, v19
	v_mul_f32_e32 v21, 0x3d372713, v11
	v_add_f32_e32 v23, 1.0, v23
	v_mul_f32_e32 v22, 0x3d372713, v16
	v_rcp_f32_e32 v24, v23
	v_mul_f32_e32 v23, 0x3d372713, v17
	v_pk_mul_f32 v[14:15], v[14:15], v[18:19]
	v_mul_f32_e32 v18, 0x3d372713, v13
	v_mul_f32_e32 v21, v11, v21
	v_mul_f32_e32 v22, v16, v22
	v_mul_f32_e32 v23, v17, v23
	v_mul_f32_e32 v18, v13, v18
	v_fma_f32 v21, v11, v21, v11
	v_fma_f32 v22, v16, v22, v16
	v_fma_f32 v23, v17, v23, v17
	v_fma_f32 v18, v13, v18, v13
	v_mul_f32_e32 v21, 0xbfcc422a, v21
	v_mul_f32_e32 v22, 0xbfcc422a, v22
	v_mul_f32_e32 v23, 0xbfcc422a, v23
	v_mul_f32_e32 v18, 0xbfcc422a, v18
	v_mul_f32_e32 v21, 0x3fb8aa3b, v21
	v_mul_f32_e32 v22, 0x3fb8aa3b, v22
	v_mul_f32_e32 v23, 0x3fb8aa3b, v23
	v_mul_f32_e32 v18, 0x3fb8aa3b, v18
	v_exp_f32_e32 v21, v21
	v_exp_f32_e32 v22, v22
	v_exp_f32_e32 v23, v23
	v_exp_f32_e32 v18, v18
	v_add_f32_e32 v21, 1.0, v21
	v_add_f32_e32 v22, 1.0, v22
	v_add_f32_e32 v23, 1.0, v23
	v_add_f32_e32 v18, 1.0, v18
	v_rcp_f32_e32 v21, v21
	v_rcp_f32_e32 v22, v22
	v_rcp_f32_e32 v23, v23
	v_rcp_f32_e32 v25, v18
	v_pk_mul_f32 v[10:11], v[10:11], v[20:21]
	v_pk_mul_f32 v[16:17], v[16:17], v[22:23]
	v_pk_mul_f32 v[12:13], v[12:13], v[24:25]
.LBB0_654:
	v_add_u32_e32 v18, 0x80000, v98
	s_mov_b32 s60, s14
	s_and_b64 vcc, exec, s[6:7]
	v_cvt_pk_bf16_f32 v14, v14, v15
	v_cvt_pk_bf16_f32 v15, v16, v17
	v_cvt_pk_bf16_f32 v16, v10, v11
	v_cvt_pk_bf16_f32 v17, v12, v13
	buffer_store_dwordx4 v[14:17], v18, s[60:63], 0 offen sc1
	s_cbranch_vccnz .LBB0_656
	v_mul_f32_e32 v11, 0x3d372713, v2
	v_mul_f32_e32 v11, v2, v11
	v_fma_f32 v11, v2, v11, v2
	v_mul_f32_e32 v11, 0xbfcc422a, v11
	v_mul_f32_e32 v11, 0x3fb8aa3b, v11
	v_exp_f32_e32 v11, v11
	v_mul_f32_e32 v10, 0x3d372713, v6
	v_mul_f32_e32 v10, v6, v10
	v_fma_f32 v10, v6, v10, v6
	v_add_f32_e32 v11, 1.0, v11
	v_rcp_f32_e32 v12, v11
	v_mul_f32_e32 v11, 0x3d372713, v7
	v_mul_f32_e32 v11, v7, v11
	v_fma_f32 v11, v7, v11, v7
	v_mul_f32_e32 v10, 0xbfcc422a, v10
	v_mul_f32_e32 v11, 0xbfcc422a, v11
	v_mul_f32_e32 v10, 0x3fb8aa3b, v10
	v_mul_f32_e32 v11, 0x3fb8aa3b, v11
	v_mul_f32_e32 v15, 0x3d372713, v4
	v_exp_f32_e32 v10, v10
	v_exp_f32_e32 v11, v11
	v_mul_f32_e32 v15, v4, v15
	v_fma_f32 v15, v4, v15, v4
	v_mul_f32_e32 v15, 0xbfcc422a, v15
	v_mul_f32_e32 v15, 0x3fb8aa3b, v15
	v_add_f32_e32 v10, 1.0, v10
	v_add_f32_e32 v11, 1.0, v11
	v_exp_f32_e32 v15, v15
	v_rcp_f32_e32 v10, v10
	v_rcp_f32_e32 v11, v11
	v_mul_f32_e32 v13, 0x3d372713, v3
	v_add_f32_e32 v15, 1.0, v15
	v_mul_f32_e32 v14, 0x3d372713, v8
	v_rcp_f32_e32 v16, v15
	v_mul_f32_e32 v15, 0x3d372713, v9
	v_pk_mul_f32 v[6:7], v[6:7], v[10:11]
	v_mul_f32_e32 v10, 0x3d372713, v5
	v_mul_f32_e32 v13, v3, v13
	v_mul_f32_e32 v14, v8, v14
	v_mul_f32_e32 v15, v9, v15
	v_mul_f32_e32 v10, v5, v10
	v_fma_f32 v13, v3, v13, v3
	v_fma_f32 v14, v8, v14, v8
	v_fma_f32 v15, v9, v15, v9
	v_fma_f32 v10, v5, v10, v5
	v_mul_f32_e32 v13, 0xbfcc422a, v13
	v_mul_f32_e32 v14, 0xbfcc422a, v14
	v_mul_f32_e32 v15, 0xbfcc422a, v15
	v_mul_f32_e32 v10, 0xbfcc422a, v10
	v_mul_f32_e32 v13, 0x3fb8aa3b, v13
	v_mul_f32_e32 v14, 0x3fb8aa3b, v14
	v_mul_f32_e32 v15, 0x3fb8aa3b, v15
	v_mul_f32_e32 v10, 0x3fb8aa3b, v10
	v_exp_f32_e32 v13, v13
	v_exp_f32_e32 v14, v14
	v_exp_f32_e32 v15, v15
	v_exp_f32_e32 v10, v10
	v_add_f32_e32 v13, 1.0, v13
	v_add_f32_e32 v14, 1.0, v14
	v_add_f32_e32 v15, 1.0, v15
	v_add_f32_e32 v10, 1.0, v10
	v_rcp_f32_e32 v13, v13
	v_rcp_f32_e32 v14, v14
	v_rcp_f32_e32 v15, v15
	v_rcp_f32_e32 v17, v10
	v_pk_mul_f32 v[2:3], v[2:3], v[12:13]
	v_pk_mul_f32 v[8:9], v[8:9], v[14:15]
	v_pk_mul_f32 v[4:5], v[4:5], v[16:17]
.LBB0_656:
	s_andn2_b64 vcc, exec, s[18:19]
	s_mov_b64 s[2:3], -1
	v_cvt_pk_bf16_f32 v6, v6, v7
	v_cvt_pk_bf16_f32 v7, v8, v9
	v_cvt_pk_bf16_f32 v8, v2, v3
	v_cvt_pk_bf16_f32 v9, v4, v5
	buffer_store_dwordx4 v[6:9], v18, s[60:63], 0 offen offset:256 sc1
	s_cbranch_vccnz .LBB0_607
	s_andn2_b64 vcc, exec, s[8:9]
	s_cbranch_vccnz .LBB0_606
	s_barrier
	s_branch .LBB0_606
